# prologue wave specialization: waves 4-7 fold pooling weights (2 tasks each) while waves 0-3 stream x to bf16+ssq, on top of v21
# speedup vs baseline: 1.0521x; 1.0096x over previous
; __device__ __forceinline__ void prologue(const Params& p, LAS unsigned char* lds) {
;     ...
;         const int gwv = blockIdx.x * 8 + wid, NGWV = gridDim.x * 8;
;         for (int it = gwv; it < 2 * 1024; it += NGWV) {
;             const int l = it >> 10, r = it & 1023, nblk = r & 15, kg = r >> 4, g = kg >> 4, c0 = (kg & 15) * 8, n = nblk * 64 + lane;
;             const float* wp = p.w_pool + ((size_t)l * 4 + g) * 128 * 128 + (size_t)c0 * 128;
;             const float* sc = p.pool_scale + l * 512 + g * 128;
;             const float* wb = p.w_br_pool + (size_t)l * 512 * DM + (size_t)(g * 128) * DM + n;
.LBB0_46:
	s_or_b64 exec, exec, s[10:11]
	s_load_dwordx16 s[52:67], s[0:1], 0x0
	s_lshl_b32 s6, s92, 3
	v_and_b32_e32 v39, 63, v222
	v_mov_b32_e32 v1, 0
	s_waitcnt lgkmcnt(0)
	v_writelane_b32 v249, s52, 4
	s_nop 1
	v_writelane_b32 v249, s53, 5
	v_writelane_b32 v249, s54, 6
	v_writelane_b32 v249, s55, 7
	v_writelane_b32 v249, s56, 8
	v_writelane_b32 v249, s57, 9
	v_writelane_b32 v249, s58, 10
	v_writelane_b32 v249, s59, 11
	v_writelane_b32 v249, s60, 12
	v_writelane_b32 v249, s61, 13
	v_writelane_b32 v249, s62, 14
	v_writelane_b32 v249, s63, 15
	v_writelane_b32 v249, s64, 16
	v_writelane_b32 v249, s65, 17
	v_writelane_b32 v249, s66, 18
	v_writelane_b32 v249, s67, 19
	s_load_dwordx16 s[52:67], s[0:1], 0x40
	s_lshl_b32 s0, s81, 3
	s_lshr_b32 s1, s17, 6
	s_add_i32 s0, s1, s0
	s_cmpk_gt_i32 s0, 0x7ff
	s_waitcnt lgkmcnt(0)
	v_writelane_b32 v249, s52, 20
	s_nop 1
	v_writelane_b32 v249, s53, 21
	v_writelane_b32 v249, s54, 22
	v_writelane_b32 v249, s55, 23
	v_writelane_b32 v249, s56, 24
	v_writelane_b32 v249, s57, 25
	v_writelane_b32 v249, s58, 26
	v_writelane_b32 v249, s59, 27
	v_writelane_b32 v249, s60, 28
	v_writelane_b32 v249, s61, 29
	v_writelane_b32 v249, s62, 30
	v_writelane_b32 v249, s63, 31
	v_writelane_b32 v249, s64, 32
	v_writelane_b32 v249, s65, 33
	v_writelane_b32 v249, s66, 34
	v_writelane_b32 v249, s67, 35
	s_cbranch_scc1 .LBB0_51
	s_lshr_b32 s32, s17, 6
	s_cmp_lt_u32 s32, 4
	s_cbranch_scc1 .LBB0_51
	s_lshl_b32 s1, s1, 6
	v_readlane_b32 s52, v249, 20
	s_add_i32 s1, s16, s1
	v_readlane_b32 s58, v249, 26
	v_readlane_b32 s59, v249, 27
	s_add_u32 s9, s58, 28
	s_addc_u32 s18, s59, 0
	s_mov_b32 s5, 0
	s_movk_i32 s19, 0x2000
	s_movk_i32 s20, 0x4000
	s_movk_i32 s21, 0x6000
	s_movk_i32 s23, 0x7000
	s_mov_b32 s24, s0
	s_lshr_b32 s32, s17, 6
	s_add_i32 s32, s32, -4
	s_lshl_b32 s24, s81, 2
	s_add_i32 s24, s24, s32
	s_lshl_b32 s1, s24, 6
	s_lshl_b32 s32, s92, 2
	s_lshl_b32 s33, s92, 8
	v_readlane_b32 s53, v249, 21
	v_readlane_b32 s54, v249, 22
	v_readlane_b32 s55, v249, 23
	v_readlane_b32 s56, v249, 24
	v_readlane_b32 s57, v249, 25
	v_readlane_b32 s60, v249, 28
	v_readlane_b32 s61, v249, 29
	v_readlane_b32 s62, v249, 30
	v_readlane_b32 s63, v249, 31
	v_readlane_b32 s64, v249, 32
	v_readlane_b32 s65, v249, 33
	v_readlane_b32 s66, v249, 34
	v_readlane_b32 s67, v249, 35

; __device__ __forceinline__ u32x4 pack8(const float* f) { u32x4 w; w.x = cvt_pk_bf16(f[0], f[1]); w.y = cvt_pk_bf16(f[2], f[3]); w.z = cvt_pk_bf16(f[4], f[5]); w.w = cvt_pk_bf16(f[6], f[7]); return w; }
; __device__ __forceinline__ void prologue(const Params& p, LAS unsigned char* lds) {
;     ...
;         for (int it = gwv; it < 2 * 1024; it += NGWV) {
;             const int l = it >> 10, r = it & 1023, nblk = r & 15, kg = r >> 4, g = kg >> 4, c0 = (kg & 15) * 8, n = nblk * 64 + lane;
;             const float* wp = p.w_pool + ((size_t)l * 4 + g) * 128 * 128 + (size_t)c0 * 128;
;             const float* sc = p.pool_scale + l * 512 + g * 128;
;             const float* wb = p.w_br_pool + (size_t)l * 512 * DM + (size_t)(g * 128) * DM + n;
;             float a[8];
; #pragma unroll
;             for (int i = 0; i < 8; ++i) a[i] = 0.f;
; #pragma unroll 8
;             for (int d = 0; d < 128; ++d) { const float x = wb[(size_t)d * DM] * sc[d];
; #pragma unroll
;                 for (int i = 0; i < 8; ++i) a[i] += wp[i * 128 + d] * x; }
;             bf16_t* dst = (bf16_t*)(p.ws + WS_W + (size_t)l * W_LAYER + WO_MIX) + (size_t)(1024 + n) * 512 + g * 128 + c0;
;             *(u32x4*)dst = pack8(a);
.LBB0_49:
	v_lshl_add_u64 v[12:13], v[2:3], 0, s[14:15]
	v_add_co_u32_e32 v14, vcc, s23, v12
	s_add_u32 s16, s26, s12
	s_nop 0
	v_addc_co_u32_e32 v15, vcc, 0, v13, vcc
	v_add_co_u32_e32 v20, vcc, s19, v12
	s_addc_u32 s17, s27, s13
	s_nop 0
	v_addc_co_u32_e32 v21, vcc, 0, v13, vcc
	v_add_co_u32_e32 v22, vcc, s20, v12
	s_add_u32 s28, s11, s12
	s_nop 0
	v_addc_co_u32_e32 v23, vcc, 0, v13, vcc
	v_add_co_u32_e32 v24, vcc, s21, v12
	s_addc_u32 s29, s25, s13
	s_nop 0
	v_addc_co_u32_e32 v25, vcc, 0, v13, vcc
	global_load_dword v37, v[14:15], off
	global_load_dword v0, v[12:13], off
	s_nop 0
	global_load_dwordx4 v[12:15], v1, s[16:17]
	global_load_dwordx4 v[16:19], v1, s[16:17] offset:16
	global_load_dword v36, v[20:21], off offset:-4096
	global_load_dword v38, v[20:21], off
	global_load_dword v88, v[22:23], off offset:-4096
	global_load_dword v89, v[22:23], off
	global_load_dword v90, v[24:25], off offset:-4096
	global_load_dword v91, v[24:25], off
	s_nop 0
	global_load_dwordx4 v[20:23], v1, s[28:29] offset:-28
	global_load_dwordx4 v[24:27], v1, s[28:29] offset:484
	global_load_dwordx4 v[28:31], v1, s[28:29] offset:996
	global_load_dwordx4 v[32:35], v1, s[28:29] offset:1508
	global_load_dwordx4 v[40:43], v1, s[28:29] offset:2020
	global_load_dwordx4 v[44:47], v1, s[28:29] offset:2532
	global_load_dwordx4 v[48:51], v1, s[28:29] offset:3044
	global_load_dwordx4 v[52:55], v1, s[28:29] offset:3556
	global_load_dwordx4 v[56:59], v1, s[28:29] offset:-12
	global_load_dwordx4 v[60:63], v1, s[28:29] offset:500
	global_load_dwordx4 v[64:67], v1, s[28:29] offset:1012
	global_load_dwordx4 v[68:71], v1, s[28:29] offset:1524
	global_load_dwordx4 v[72:75], v1, s[28:29] offset:2036
	global_load_dwordx4 v[76:79], v1, s[28:29] offset:2548
	global_load_dwordx4 v[80:83], v1, s[28:29] offset:3060
	global_load_dwordx4 v[84:87], v1, s[28:29] offset:3572
	s_add_u32 s14, s14, 0x8000
	s_addc_u32 s15, s15, 0
	s_add_u32 s12, s12, 32
	s_addc_u32 s13, s13, 0
	s_cmp_eq_u32 s14, 0x80000
	s_waitcnt vmcnt(23)
	v_mul_f32_e32 v0, v0, v12
	s_waitcnt vmcnt(21)
	v_mul_f32_e32 v12, v36, v13
	s_waitcnt vmcnt(20)
	v_mul_f32_e32 v14, v38, v14
	s_waitcnt vmcnt(19)
	v_mul_f32_e32 v36, v88, v15
	s_waitcnt vmcnt(18)
	v_mul_f32_e32 v16, v89, v16
	s_waitcnt vmcnt(17)
	v_mul_f32_e32 v38, v90, v17
	s_waitcnt vmcnt(16)
	v_mul_f32_e32 v18, v91, v18
	s_waitcnt vmcnt(15)
	v_mov_b32_e32 v90, v20
	s_waitcnt vmcnt(14)
	v_mov_b32_e32 v91, v24
	v_mov_b32_e32 v24, v21
	v_mov_b32_e32 v20, v22
	v_mov_b32_e32 v21, v26
	v_mov_b32_e32 v26, v23
	s_waitcnt vmcnt(13)
	v_mov_b32_e32 v22, v28
	s_waitcnt vmcnt(12)
	v_mov_b32_e32 v23, v32
	v_mov_b32_e32 v32, v29
	v_mov_b32_e32 v28, v30
	v_mov_b32_e32 v29, v34
	v_mov_b32_e32 v34, v31
	s_waitcnt vmcnt(11)
	v_mov_b32_e32 v30, v40
	s_waitcnt vmcnt(10)
	v_mov_b32_e32 v31, v44
	v_mov_b32_e32 v44, v41
	v_mov_b32_e32 v40, v42
	v_mov_b32_e32 v41, v46
	v_mov_b32_e32 v46, v43
	s_waitcnt vmcnt(9)
	v_mov_b32_e32 v42, v48
	s_waitcnt vmcnt(8)
	v_mov_b32_e32 v43, v52
	v_mov_b32_e32 v52, v49
	v_pk_fma_f32 v[10:11], v[0:1], v[90:91], v[10:11] op_sel_hi:[0,1,1]
	v_pk_fma_f32 v[8:9], v[0:1], v[22:23], v[8:9] op_sel_hi:[0,1,1]
	v_pk_fma_f32 v[6:7], v[0:1], v[30:31], v[6:7] op_sel_hi:[0,1,1]
	v_pk_fma_f32 v[4:5], v[0:1], v[42:43], v[4:5] op_sel_hi:[0,1,1]
	v_mov_b32_e32 v48, v50
	v_mov_b32_e32 v49, v54
	v_pk_fma_f32 v[10:11], v[12:13], v[24:25], v[10:11] op_sel_hi:[0,1,1]
	v_pk_fma_f32 v[8:9], v[12:13], v[32:33], v[8:9] op_sel_hi:[0,1,1]
	v_pk_fma_f32 v[6:7], v[12:13], v[44:45], v[6:7] op_sel_hi:[0,1,1]
	v_pk_fma_f32 v[4:5], v[12:13], v[52:53], v[4:5] op_sel_hi:[0,1,1]
	v_mov_b32_e32 v54, v51
	v_pk_fma_f32 v[10:11], v[14:15], v[20:21], v[10:11] op_sel_hi:[0,1,1]
	v_pk_fma_f32 v[8:9], v[14:15], v[28:29], v[8:9] op_sel_hi:[0,1,1]
	v_pk_fma_f32 v[6:7], v[14:15], v[40:41], v[6:7] op_sel_hi:[0,1,1]
	v_pk_fma_f32 v[4:5], v[14:15], v[48:49], v[4:5] op_sel_hi:[0,1,1]
	s_waitcnt vmcnt(7)
	v_mov_b32_e32 v50, v56
	s_waitcnt vmcnt(6)
	v_mov_b32_e32 v51, v60
	v_mov_b32_e32 v60, v57
	v_mov_b32_e32 v56, v58
	v_mov_b32_e32 v57, v62
	v_mov_b32_e32 v62, v59
	s_waitcnt vmcnt(5)
	v_mov_b32_e32 v58, v64
	s_waitcnt vmcnt(4)
	v_mov_b32_e32 v59, v68
	v_mov_b32_e32 v68, v65
	v_mov_b32_e32 v64, v66
	v_mov_b32_e32 v65, v70
	v_mov_b32_e32 v70, v67
	s_waitcnt vmcnt(3)
	v_mov_b32_e32 v66, v72
	s_waitcnt vmcnt(2)
	v_mov_b32_e32 v67, v76
	v_mov_b32_e32 v76, v73
	v_mov_b32_e32 v72, v74
	v_mov_b32_e32 v73, v78
	v_mov_b32_e32 v78, v75
	s_waitcnt vmcnt(1)
	v_mov_b32_e32 v74, v80
	s_waitcnt vmcnt(0)
	v_mov_b32_e32 v75, v84
	v_pk_fma_f32 v[10:11], v[36:37], v[26:27], v[10:11] op_sel_hi:[0,1,1]
	v_pk_fma_f32 v[8:9], v[36:37], v[34:35], v[8:9] op_sel_hi:[0,1,1]
	v_pk_fma_f32 v[6:7], v[36:37], v[46:47], v[6:7] op_sel_hi:[0,1,1]
	v_pk_fma_f32 v[4:5], v[36:37], v[54:55], v[4:5] op_sel_hi:[0,1,1]
	v_mov_b32_e32 v84, v81
	v_pk_fma_f32 v[10:11], v[16:17], v[50:51], v[10:11] op_sel_hi:[0,1,1]
	v_pk_fma_f32 v[8:9], v[16:17], v[58:59], v[8:9] op_sel_hi:[0,1,1]
	v_pk_fma_f32 v[6:7], v[16:17], v[66:67], v[6:7] op_sel_hi:[0,1,1]
	v_pk_fma_f32 v[4:5], v[16:17], v[74:75], v[4:5] op_sel_hi:[0,1,1]
	v_mov_b32_e32 v80, v82
	v_mov_b32_e32 v81, v86
	v_pk_fma_f32 v[10:11], v[38:39], v[60:61], v[10:11] op_sel_hi:[0,1,1]
	v_pk_fma_f32 v[8:9], v[38:39], v[68:69], v[8:9] op_sel_hi:[0,1,1]
	v_pk_fma_f32 v[6:7], v[38:39], v[76:77], v[6:7] op_sel_hi:[0,1,1]
	v_pk_fma_f32 v[4:5], v[38:39], v[84:85], v[4:5] op_sel_hi:[0,1,1]
	v_mul_f32_e32 v88, v37, v19
	v_mov_b32_e32 v86, v83
	v_pk_fma_f32 v[10:11], v[18:19], v[56:57], v[10:11] op_sel_hi:[0,1,1]
	v_pk_fma_f32 v[8:9], v[18:19], v[64:65], v[8:9] op_sel_hi:[0,1,1]
	v_pk_fma_f32 v[6:7], v[18:19], v[72:73], v[6:7] op_sel_hi:[0,1,1]
	v_pk_fma_f32 v[4:5], v[18:19], v[80:81], v[4:5] op_sel_hi:[0,1,1]
	v_pk_fma_f32 v[10:11], v[88:89], v[62:63], v[10:11] op_sel_hi:[0,1,1]
	v_pk_fma_f32 v[8:9], v[88:89], v[70:71], v[8:9] op_sel_hi:[0,1,1]
	v_pk_fma_f32 v[6:7], v[88:89], v[78:79], v[6:7] op_sel_hi:[0,1,1]
	v_pk_fma_f32 v[4:5], v[88:89], v[86:87], v[4:5] op_sel_hi:[0,1,1]
	s_cbranch_scc0 .LBB0_49
	s_lshl_b32 s11, s24, 6
	s_and_b32 s11, s11, 0x3c0
	s_and_b32 s4, s4, 3
	v_or_b32_e32 v0, s11, v39
	s_mul_hi_i32 s11, s10, 0x1b00000
	s_mul_i32 s10, s10, 0x1b00000
	s_add_u32 s10, s50, s10
	s_addc_u32 s11, s51, s11
	v_lshlrev_b32_e32 v0, 10, v0
	v_lshl_add_u64 v[2:3], s[10:11], 0, v[0:1]
	s_lshl_b32 s4, s4, 8
	v_lshl_add_u64 v[2:3], v[2:3], 0, s[4:5]
	s_and_b32 s4, s24, 0xf0
	v_lshl_add_u64 v[2:3], v[2:3], 0, s[4:5]
	v_add_co_u32_e32 v2, vcc, 0x880000, v2
	s_add_i32 s24, s24, s32
	s_add_i32 s1, s1, s33
	v_addc_co_u32_e32 v3, vcc, 0, v3, vcc
	s_cmpk_gt_i32 s24, 0x7ff
	v_cvt_pk_bf16_f32 v10, v10, v11
	v_cvt_pk_bf16_f32 v11, v8, v9
	v_cvt_pk_bf16_f32 v12, v6, v7
	v_cvt_pk_bf16_f32 v13, v4, v5
	global_store_dwordx4 v[2:3], v[10:13], off
	s_cbranch_scc0 .LBB0_48

; __device__ __forceinline__ void prologue(const Params& p, LAS unsigned char* lds) {
;     ...
;     {
;         bf16_t* XB = (bf16_t*)(p.ws + WS_XB);
;         const int gw = blockIdx.x * 8 + wid, NGW = gridDim.x * 8;
; #pragma unroll 1
;         for (int m0 = gw; m0 < MREAL; m0 += 4 * NGW) {
;             f32x4 v[4][4];
; #pragma unroll
;             for (int r = 0; r < 4; ++r) { const int m = m0 + r * NGW;
;                 if (m < MREAL) { const f32x4* xr = (const f32x4*)(m < MP ? p.xp + (size_t)m * DM : p.xs + (size_t)(m - MP) * DM) + lane;
; #pragma unroll
;                     for (int j = 0; j < 4; ++j) v[r][j] = xr[64 * j]; } }
.LBB0_65:
	v_readfirstlane_b32 s32, v222
	v_mbcnt_lo_u32_b32 v68, -1, 0
	s_lshr_b32 s32, s32, 6
	s_cmp_gt_u32 s32, 3
	s_cbranch_scc1 .LBB0_88
	s_lshl_b32 s0, s81, 2
	s_add_i32 s0, s0, s32
	s_lshl_b32 s6, s92, 2
	s_cmp_gt_i32 s0, 0x807f
	s_cbranch_scc1 .LBB0_88
	v_lshlrev_b32_e32 v64, 3, v39
	v_mov_b32_e32 v65, 0
	v_lshl_add_u64 v[0:1], s[50:51], 0, v[64:65]
	s_mov_b64 s[4:5], 0x3800000
	v_lshl_add_u64 v[66:67], v[0:1], 0, s[4:5]
	v_cmp_eq_u32_e64 s[4:5], 0, v39
	s_lshl_b32 s23, s92, 3
	s_mul_i32 s24, s92, 12
	v_lshlrev_b32_e32 v64, 4, v39
	v_mbcnt_hi_u32_b32 v69, -1, v68
	s_branch .LBB0_69

; __device__ __forceinline__ unsigned xb_ld(unsigned* p)              { return __hip_atomic_load(p, __ATOMIC_RELAXED, __HIP_MEMORY_SCOPE_AGENT); }
; __device__ __forceinline__ unsigned xb_add(unsigned* p, unsigned v) { return __hip_atomic_fetch_add(p, v, __ATOMIC_RELAXED, __HIP_MEMORY_SCOPE_AGENT); }
; __device__ __forceinline__ void xcd_barrier_complete(unsigned* bar, unsigned x, unsigned& nloc, unsigned& nx) {
;     const unsigned G = gridDim.x * gridDim.y * gridDim.z;
;     unsigned sum, cnt, mine, sp = 0u;
;     for (;;) {
;         sum = 0u; cnt = 0u; mine = 0u;
; #pragma unroll
;         for (unsigned j = 0; j < 16; ++j) { const unsigned c = xb_ld(&bar[XB_XCNT(j)]); sum += c; cnt += (c > 0u) ? 1u : 0u; mine = (j == x) ? c : mine; }
; __device__ __forceinline__ void xcd_barrier(const XcdBarrier& b) {
;     asm volatile("s_waitcnt vmcnt(0)" ::: "memory");
;     __syncthreads();
;     if (threadIdx.x == 0) {
;         unsigned* bar = b.bar;
;         __builtin_amdgcn_s_waitcnt(0);
;         unsigned nloc = b.st[0], nx = b.st[1];
;         if (nloc == 0u) { xcd_barrier_complete(bar, b.x, nloc, nx); b.st[0] = nloc; b.st[1] = nx; }
;         const unsigned old = xb_add(&bar[XB_XSUB(b.x)], 1u);
.LBB0_88:
	s_lshl_b32 s6, s92, 3
	s_add_u32 s18, s50, 0xc0200
	s_mul_i32 s0, s93, s92
	s_addc_u32 s19, s51, 0
	s_mul_i32 s33, s0, s7
	s_add_u32 s0, s50, 0xc0400
	s_addc_u32 s1, s51, 0
	v_writelane_b32 v249, s0, 36
	s_waitcnt vmcnt(0)
	s_waitcnt lgkmcnt(0)
	s_barrier
	v_writelane_b32 v249, s1, 37
	s_add_u32 s0, s50, 0xc0500
	s_addc_u32 s1, s51, 0
	v_writelane_b32 v249, s0, 38
	s_nop 1
	v_writelane_b32 v249, s1, 39
	s_add_u32 s0, s50, 0xc0600
	s_addc_u32 s1, s51, 0
	v_writelane_b32 v249, s0, 40
	s_nop 1
	v_writelane_b32 v249, s1, 41
	s_add_u32 s0, s50, 0xc0700
	s_addc_u32 s1, s51, 0
	v_writelane_b32 v249, s0, 42
	s_nop 1
	v_writelane_b32 v249, s1, 43
	s_add_u32 s0, s50, 0xc0800
	s_addc_u32 s1, s51, 0
	v_writelane_b32 v249, s0, 44
	s_nop 1
	v_writelane_b32 v249, s1, 45
	s_add_u32 s0, s50, 0xc0900
	s_addc_u32 s1, s51, 0
	v_writelane_b32 v249, s0, 46
	s_nop 1
	v_writelane_b32 v249, s1, 47
	s_add_u32 s0, s50, 0xc0a00
	s_addc_u32 s1, s51, 0
	v_writelane_b32 v249, s0, 48
	s_nop 1
	v_writelane_b32 v249, s1, 49
	s_add_u32 s0, s50, 0xc0b00
	s_addc_u32 s1, s51, 0
	v_writelane_b32 v249, s0, 50
	s_nop 1
	v_writelane_b32 v249, s1, 51
	s_add_u32 s0, s50, 0xc0c00
	s_addc_u32 s1, s51, 0
	v_writelane_b32 v249, s0, 52
	s_nop 1
	v_writelane_b32 v249, s1, 53
	s_add_u32 s0, s50, 0xc0d00
	s_addc_u32 s1, s51, 0
	v_writelane_b32 v249, s0, 54
	s_nop 1
	v_writelane_b32 v249, s1, 55
	s_add_u32 s0, s50, 0xc0e00
	s_addc_u32 s1, s51, 0
	v_writelane_b32 v249, s0, 56
	s_nop 1
	v_writelane_b32 v249, s1, 57
	s_add_u32 s0, s50, 0xc0f00
	s_addc_u32 s1, s51, 0
	v_writelane_b32 v249, s0, 58
	s_nop 1
	v_writelane_b32 v249, s1, 59
	s_add_u32 s0, s50, 0xc1000
	s_addc_u32 s1, s51, 0
	v_writelane_b32 v249, s0, 60
	s_nop 1
	v_writelane_b32 v249, s1, 61
	s_add_u32 s0, s50, 0xc1100
	s_addc_u32 s1, s51, 0
	v_writelane_b32 v249, s0, 62
	s_nop 1
	v_writelane_b32 v249, s1, 63
	s_add_u32 s0, s50, 0xc1200
	s_addc_u32 s1, s51, 0
	v_writelane_b32 v248, s0, 0
	s_nop 1
	v_writelane_b32 v248, s1, 1
	s_add_u32 s0, s50, 0xc1300
	s_addc_u32 s1, s51, 0
	v_writelane_b32 v248, s0, 2
	s_cmp_eq_u32 s22, 15
	s_nop 0
	v_writelane_b32 v248, s1, 3
	s_cselect_b64 s[0:1], -1, 0
	v_writelane_b32 v248, s0, 4
	s_cmp_eq_u32 s22, 14
	s_nop 0
	v_writelane_b32 v248, s1, 5
	s_cselect_b64 s[0:1], -1, 0
	v_writelane_b32 v248, s0, 6
	s_cmp_eq_u32 s22, 13
	s_nop 0
	v_writelane_b32 v248, s1, 7
	s_cselect_b64 s[0:1], -1, 0
	v_writelane_b32 v248, s0, 8
	s_cmp_eq_u32 s22, 12
	s_nop 0
	v_writelane_b32 v248, s1, 9
	s_cselect_b64 s[0:1], -1, 0
	v_writelane_b32 v248, s0, 10
	s_cmp_eq_u32 s22, 11
	s_nop 0
	v_writelane_b32 v248, s1, 11
	s_cselect_b64 s[0:1], -1, 0
	v_writelane_b32 v248, s0, 12
	s_cmp_eq_u32 s22, 10
	s_nop 0
	v_writelane_b32 v248, s1, 13
	s_cselect_b64 s[0:1], -1, 0
	v_writelane_b32 v248, s0, 14
	s_cmp_eq_u32 s22, 9
	s_nop 0
	v_writelane_b32 v248, s1, 15
	s_cselect_b64 s[0:1], -1, 0
	v_writelane_b32 v248, s0, 16
	s_cmp_eq_u32 s22, 8
	s_nop 0
	v_writelane_b32 v248, s1, 17
	s_cselect_b64 s[0:1], -1, 0
	v_writelane_b32 v248, s0, 18
	s_cmp_eq_u32 s22, 7
	s_nop 0
	v_writelane_b32 v248, s1, 19
	s_cselect_b64 s[0:1], -1, 0
	v_writelane_b32 v248, s0, 20
	s_cmp_eq_u32 s22, 6
	s_nop 0
	v_writelane_b32 v248, s1, 21
	s_cselect_b64 s[0:1], -1, 0
	v_writelane_b32 v248, s0, 22
	s_cmp_eq_u32 s22, 5
	s_nop 0
	v_writelane_b32 v248, s1, 23
	s_cselect_b64 s[0:1], -1, 0
	v_writelane_b32 v248, s0, 24
	s_cmp_eq_u32 s22, 4
	s_nop 0
	v_writelane_b32 v248, s1, 25
	s_cselect_b64 s[0:1], -1, 0
	v_writelane_b32 v248, s0, 26
	s_cmp_eq_u32 s22, 3
	s_nop 0
	v_writelane_b32 v248, s1, 27
	s_cselect_b64 s[0:1], -1, 0
	v_writelane_b32 v248, s0, 28
	s_cmp_eq_u32 s22, 2
	s_nop 0
	v_writelane_b32 v248, s1, 29
	s_cselect_b64 s[0:1], -1, 0
	v_writelane_b32 v248, s0, 30
	s_cmp_eq_u32 s22, 1
	s_nop 0
	v_writelane_b32 v248, s1, 31
	s_cselect_b64 s[0:1], -1, 0
	v_writelane_b32 v248, s0, 32
	s_cmp_eq_u32 s22, 0
	s_nop 0
	v_writelane_b32 v248, s1, 33
	s_cselect_b64 s[0:1], -1, 0
	v_writelane_b32 v248, s0, 34
	s_nop 1
	v_writelane_b32 v248, s1, 35
	s_lshl_b32 s0, s22, 8
	s_add_u32 s0, s2, s0
	s_addc_u32 s1, s3, 0
	s_add_u32 s2, s0, 0x1400
	s_addc_u32 s3, s1, 0
	v_writelane_b32 v248, s2, 36
	s_add_u32 s0, s0, 0x2400
	s_addc_u32 s1, s1, 0
	v_writelane_b32 v248, s3, 37
	v_writelane_b32 v248, s0, 38
	s_nop 1
	v_writelane_b32 v248, s1, 39
	s_add_u32 s0, s50, 0xc3400
	s_addc_u32 s1, s51, 0
	v_writelane_b32 v248, s0, 40
	s_nop 1
	v_writelane_b32 v248, s1, 41
	s_add_u32 s0, s50, 0xc3500
	s_addc_u32 s1, s51, 0
	v_writelane_b32 v248, s0, 42
	s_nop 1
	v_writelane_b32 v248, s1, 43
	s_mov_b64 s[0:1], exec
	v_readlane_b32 s2, v249, 2
	v_readlane_b32 s3, v249, 3
	s_and_b64 s[2:3], s[0:1], s[2:3]
	s_mov_b64 exec, s[2:3]
	s_cbranch_execz .LBB0_140
	s_add_i32 s2, 0, 0x23fc0
	v_mov_b32_e32 v0, s2
	s_waitcnt vmcnt(0) expcnt(0) lgkmcnt(0)
	ds_read_b32 v2, v0
	s_add_i32 s2, 0, 0x23fc4
	v_mov_b32_e32 v0, s2
	ds_read_b32 v0, v0
	s_waitcnt lgkmcnt(1)
	v_cmp_ne_u32_e32 vcc, 0, v2
	s_cbranch_vccnz .LBB0_104
	s_mov_b32 s7, 1
	v_mov_b32_e32 v16, 0
	s_branch .LBB0_92
